# first grid sync by a device-scope arrival counter instead of cooperative-groups sync; SBA early-exit block-AND via two alternating LDS flags (1 barrier instead of 3)
# speedup vs baseline: 1.0667x; 1.0111x over previous
; __global__ void __launch_bounds__(512, 2) hybrid_megakernel(KArgs ka) {
.LBB0_243:
	s_or_b64 exec, exec, s[10:11]
	v_readlane_b32 s84, v253, 46
	s_cmp_lt_i32 s75, 1
	s_mov_b64 s[96:97], s[36:37]
	s_mov_b64 s[42:43], s[90:91]
	v_readlane_b32 s85, v253, 47
	s_cbranch_scc1 .LBB0_259
	v_lshrrev_b32_e32 v1, 20, v0
	v_lshrrev_b32_e32 v2, 10, v0
	v_or_b32_e32 v1, v2, v1
	s_movk_i32 s0, 0x3ff
	v_and_or_b32 v1, v1, s0, v192
	v_cmp_eq_u32_e32 vcc, 0, v1
	s_barrier
	s_and_saveexec_b64 s[4:5], vcc
	s_cbranch_execz .LBB0_254
	buffer_wbl2 sc1
	s_waitcnt vmcnt(0)
	s_load_dword s8, s[96:97], 0xb0
	v_mov_b32_e32 v3, 0
	v_mov_b32_e32 v4, 1
	s_add_u32 s6, s72, 0x19008400
	s_addc_u32 s7, s73, 0
	s_mov_b32 s10, 0
	global_atomic_add v3, v4, s[6:7] offset:16
	s_waitcnt lgkmcnt(0)
.Lgs_spin:
	s_sleep 1
	global_load_dword v1, v3, s[6:7] offset:16 sc1
	s_add_u32 s10, s10, 1
	s_waitcnt vmcnt(0)
	v_readfirstlane_b32 s9, v1
	s_cmp_ge_u32 s10, 0x400000
	s_cbranch_scc1 .Lgs_done
	s_cmp_lt_u32 s9, s8
	s_cbranch_scc1 .Lgs_spin

; __device__ __forceinline__ int rho_row(int k) { return (k & 32) | ((k & 4) << 2) | ((k & 24) >> 1) | (k & 3); }
; __device__ __forceinline__ void phase_sba_attn(const Params& p, u16* sm) {
;     ...
;   for (int tile = blockIdx.x; tile < ntiles; tile += gridDim.x) {
;     const int qt = 31 - (tile >> 7), bh = tile & 127;
;     const int b = bh >> 4, h = bh & 15;
;     const int myq = qt * 128 + wave * 16 + fr;
;     bf16x8 qf[2];
; #pragma unroll
;     for (int ks = 0; ks < 2; ++ks) qf[ks] = *(const bf16x8*)(p.qb + ((size_t)b * SEQ + myq) * DM + h * 64 + ks * 32 + fq * 8);
;     f32x4 o[4];
; #pragma unroll
;     for (int dm = 0; dm < 4; ++dm) o[dm] = (f32x4){0.f, 0.f, 0.f, 0.f};
;     float carry = 0.f;
;     const int pc = tid & 7, pr = tid >> 3, prl = rho_row(pr);
;     const u16* kbase = p.kb + ((size_t)b * SEQ) * DM + h * 64 + (size_t)pr * DM + pc * 8;
;     const u16* vbase = p.vT + ((size_t)(b * 16 + h) * 64 + pr) * SEQ + pc * 8;
;     uint4 rk = *(const uint4*)(kbase + (size_t)(2 * qt + 1) * 64 * DM);
;     uint4 rv = *(const uint4*)(vbase + (2 * qt + 1) * 64);
;     int buf = 0;
;     ...
;       u16* sK = sK0 + buf * 2 * 64 * LDSP; u16* sV = sV0 + buf * 2 * 64 * LDSP;
;       *(uint4*)(sK + prl * LDSP + pc * 8) = rk;
;       *(uint4*)(sV + pr * LDSP + pc * 8) = rv;
;       if (kt > 0) { rk = *(const uint4*)(kbase + (size_t)(kt - 1) * 64 * DM); rv = *(const uint4*)(vbase + (kt - 1) * 64); }
;       buf ^= 1;
;       __syncthreads();
;     ...
;       if (__syncthreads_and(carry < -150.1f)) break;
.LBB0_324:
	v_readfirstlane_b32 s8, v192
	v_mov_b32_e32 v2, 1
	s_nop 1
	s_cmp_ge_u32 s8, 64
	s_cbranch_scc1 .Lsba_noinit
	s_mov_b64 s[8:9], exec
	s_mov_b64 exec, 1
	ds_write_b32 v110, v2 offset:16
	ds_write_b32 v110, v2 offset:32
	s_mov_b64 exec, s[8:9]
.Lsba_noinit:
	s_ashr_i32 s8, s3, 7
	s_sub_i32 s10, 31, s8
	s_lshl_b32 s11, s10, 7
	v_add_u32_e32 v71, s11, v95
	s_lshl_b32 s17, s3, 6
	s_bfe_u32 s8, s3, 0x30004
	v_or_b32_e32 v113, v71, v61
	s_and_b32 s23, s17, 0x3c0
	v_lshl_add_u32 v0, s8, 12, v113
	s_lshl_b32 s20, s23, 1
	s_lshl_b32 s8, s8, 23
	v_lshlrev_b64 v[72:73], 11, v[0:1]
	s_add_u32 s8, s14, s8
	v_lshl_add_u64 v[2:3], s[52:53], 0, v[72:73]
	s_addc_u32 s9, s15, 0
	v_lshl_add_u64 v[2:3], v[2:3], 0, s[20:21]
	s_add_u32 s8, s8, s20
	v_lshl_add_u64 v[2:3], v[2:3], 0, v[64:65]
	s_addc_u32 s9, s9, 0
	global_load_dwordx4 v[12:15], v[2:3], off
	global_load_dwordx4 v[16:19], v[2:3], off offset:64
	v_lshl_add_u64 v[2:3], s[8:9], 0, v[62:63]
	s_and_b32 s8, s17, 0x1fc0
	s_lshl_b32 s24, s10, 1
	v_add_lshl_u32 v0, s8, v94, 13
	s_or_b32 s8, s24, 1
	v_lshl_add_u64 v[76:77], v[66:67], 0, v[0:1]
	s_lshl_b32 s20, s8, 7
	s_mov_b32 s9, s21
	v_lshl_add_u64 v[74:75], v[2:3], 0, v[68:69]
	v_lshl_add_u64 v[2:3], v[76:77], 0, s[20:21]
	s_lshl_b64 s[8:9], s[8:9], 17
	v_lshl_add_u64 v[20:21], v[74:75], 0, s[8:9]
	global_load_dwordx4 v[32:35], v[2:3], off
	global_load_dwordx4 v[28:31], v[20:21], off
	v_mov_b32_e32 v2, v1
	v_mov_b32_e32 v3, v1
	v_mov_b32_e32 v0, v1
	v_mov_b64_e32 v[42:43], v[2:3]
	v_mov_b64_e32 v[38:39], v[2:3]
	v_mov_b64_e32 v[26:27], v[2:3]
	v_mov_b64_e32 v[22:23], v[2:3]
	v_or_b32_e32 v114, 15, v71
	s_mov_b32 s20, s11
	v_mov_b64_e32 v[40:41], v[0:1]
	v_mov_b64_e32 v[36:37], v[0:1]
	v_mov_b64_e32 v[24:25], v[0:1]
	v_mov_b64_e32 v[20:21], v[0:1]
	v_mov_b32_e32 v0, 0
	s_mov_b32 s28, s21
	s_branch .LBB0_327
.LBB0_326:
	s_xor_b32 s28, s28, 1
	s_cmp_lg_u32 s24, -1
	v_cmp_eq_u32_e32 vcc, 0, v2
	s_cselect_b64 s[8:9], -1, 0
	s_and_b64 s[8:9], s[8:9], vcc
	s_sub_i32 s20, s20, 64
	s_add_i32 s24, s24, -1
	s_and_b64 vcc, exec, s[8:9]
	s_cbranch_vccz .LBB0_323

; __device__ __forceinline__ void phase_sba_attn(const Params& p, u16* sm) {
;     ...
;       if (__syncthreads_and(carry < -150.1f)) break;
.LBB0_336:
	s_or_b64 exec, exec, s[26:27]
	v_cmp_gt_f32_e32 vcc, s1, v0
	v_readfirstlane_b32 s9, v192
	s_lshl_b32 s8, s28, 4
	v_mov_b32_e32 v2, 0
	v_add_u32_e32 v3, s8, v110
	s_cmp_eq_u64 vcc, exec
	s_mov_b64 s[18:19], exec
	s_cbranch_scc1 .Lsba_keep
	s_mov_b64 exec, 1
	ds_write_b32 v3, v2 offset:16
	s_mov_b64 exec, s[18:19]
.Lsba_keep:
	s_cmp_ge_u32 s9, 64
	s_cbranch_scc1 .Lsba_norearm
	v_mov_b32_e32 v2, 1
	v_xor_b32_e32 v44, 16, v3
	s_mov_b64 exec, 1
	ds_write_b32 v44, v2 offset:16
	s_mov_b64 exec, s[18:19]
.Lsba_norearm:
	s_waitcnt lgkmcnt(0)
	s_barrier
	ds_read_b32 v2, v3 offset:16
	s_waitcnt lgkmcnt(0)
	s_branch .LBB0_326
